# even scans: wait for the prefetched raw inputs moved from the interval top to just before stage2 (after next prefetch issue and output stores)
# speedup vs baseline: 1.0004x; 1.0004x over previous
; __device__ __forceinline__ unsigned pk2(float lo, float hi) { f32x2_t v = {lo, hi}; bf16x2_t b = __builtin_convertvector(v, bf16x2_t); return __builtin_bit_cast(unsigned, b); }
; __device__ __forceinline__ bf16_t f2bf(float f) { return (bf16_t)(pk2(f, 0.f) & 0xffffu); }
; __device__ __forceinline__ float lo_bf(unsigned u) { return __uint_as_float(u << 16); }
; __device__ __forceinline__ float hi_bf(unsigned u) { return __uint_as_float(u & 0xffff0000u); }
; __device__ __forceinline__ float sigmoidf_(float x) { return __builtin_amdgcn_rcpf(1.f + __expf(-x)); }
; __device__ __forceinline__ float siluf_(float x) { return x * __builtin_amdgcn_rcpf(1.f + __expf(-x)); }
; template <int MODE>
; __device__ void scan_unit(int swave, const Params& p, int j, int b, int h, int dir, char* shm) {
;     ...
;       } else {
;         const float f0 = lbv0 + (1.f - lbv0) * sigmoidf_(lo_bf(R.k)), f1 = lbv1 + (1.f - lbv1) * sigmoidf_(hi_bf(R.k));
;         g0 = __logf(fmaxf(f0, 1e-20f)); g1 = __logf(fmaxf(f1, 1e-20f));
;       }
;       float s0, s1;
;       const float cum0 = row_scan(g0, s0), cum1 = row_scan(g1, s1);
;       float q0, q1, k0, k1;
;       if (MODE == 0) { q0 = lo_bf(R.q); q1 = hi_bf(R.q); k0 = lo_bf(R.k) * 0.125f; k1 = hi_bf(R.k) * 0.125f; }
;       else { q0 = siluf_(lo_bf(R.q)); q1 = siluf_(hi_bf(R.q)); k0 = (1.f - lbv0) * sigmoidf_(-lo_bf(R.k)); k1 = (1.f - lbv1) * sigmoidf_(-hi_bf(R.k)); }
;       *(unsigned*)(qin + ti * QS + dp) = pk2(q0 * __expf(cum0), q1 * __expf(cum1));
;       *(unsigned*)(ktil + ti * QS + dp) = pk2(k0 * __expf(-cum0), k1 * __expf(-cum1));
;       koutT[dp * 16 + ti] = f2bf(k0 * __expf(s0 - cum0));
;       koutT[(dp + 1) * 16 + ti] = f2bf(k1 * __expf(s1 - cum1));
;       if (ti == 0) *(float2*)(dec + dp) = make_float2(__expf(s0), __expf(s1));
;     ...
;   auto body = [&](int it, Raw& c0, Raw& c1, Raw& n0, Raw& n1) {
;     touch(c0); touch(c1);
;     __builtin_amdgcn_sched_barrier(0);
;     const int cA = 2 * it + 4 < NCH ? 2 * it + 4 : NCH - 2;
;     load_raw(cA, n0); load_raw(cA + 1, n1);
;     if (it > 0) { ostore(2 * it - 2, obp((it - 1) & 1, 0)); ostore(2 * it - 1, obp((it - 1) & 1, 1)); }
;     stage2(c0, bufp((it + 1) & 1, 0), 0); stage2(c1, bufp((it + 1) & 1, 1), 0);
.LBB0_647:
	s_cmp_gt_u32 s35, 61
	s_cselect_b64 s[74:75], -1, 0
	s_lshl_b32 s20, s35, 5
	s_add_i32 s18, s20, 64
	s_cmp_lt_u32 s35, 62
	s_cselect_b64 s[2:3], -1, 0
	s_and_b64 s[16:17], s[2:3], exec
	s_cselect_b32 s16, s18, 0x7e0
	v_or_b32_e32 v2, s16, v37
	v_sub_u32_e32 v0, 0x7ff, v2
	v_cndmask_b32_e64 v0, v0, v2, s[0:1]
	v_ashrrev_i32_e32 v1, 31, v0
	v_lshl_add_u64 v[0:1], s[46:47], 0, v[0:1]
	v_mov_b64_e32 v[32:33], s[48:49]
	v_mad_u64_u32 v[34:35], s[16:17], v0, s53, v[32:33]
	v_mad_i32_i24 v35, v1, s53, v35
	v_lshl_add_u64 v[60:61], v[34:35], 0, s[94:95]
	v_or_b32_e32 v2, 16, v2
	v_lshl_add_u64 v[60:61], v[60:61], 0, s[50:51]
	v_sub_u32_e32 v56, 0x7ff, v2
	v_lshl_add_u64 v[62:63], v[60:61], 0, v[22:23]
	v_cndmask_b32_e64 v60, v56, v2, s[0:1]
	v_ashrrev_i32_e32 v61, 31, v60
	v_lshl_add_u64 v[60:61], s[46:47], 0, v[60:61]
	v_mad_u64_u32 v[32:33], s[16:17], v60, s53, v[32:33]
	v_lshl_add_u64 v[0:1], v[34:35], 0, s[50:51]
	v_lshl_add_u64 v[34:35], v[34:35], 0, s[72:73]
	v_mad_i32_i24 v33, v61, s53, v33
	v_lshl_add_u64 v[34:35], v[34:35], 0, v[26:27]
	v_lshl_add_u64 v[60:61], v[32:33], 0, s[50:51]
	v_add_co_u32_e32 v34, vcc, s62, v34
	v_lshl_add_u64 v[64:65], v[60:61], 0, v[22:23]
	v_lshl_add_u64 v[60:61], v[32:33], 0, s[94:95]
	v_lshl_add_u64 v[0:1], v[0:1], 0, v[22:23]
	v_addc_co_u32_e32 v35, vcc, 0, v35, vcc
	v_lshl_add_u64 v[60:61], v[60:61], 0, s[50:51]
	v_lshl_add_u64 v[66:67], v[60:61], 0, v[22:23]
	global_load_dword v60, v[0:1], off offset:3136
	global_load_dword v61, v[62:63], off
	s_nop 0
	global_load_dwordx2 v[34:35], v[34:35], off offset:576
	s_nop 0
	global_load_dword v56, v[64:65], off offset:3136
	global_load_dword v58, v[66:67], off
	v_lshl_add_u64 v[0:1], v[32:33], 0, s[72:73]
	v_lshl_add_u64 v[0:1], v[0:1], 0, v[26:27]
	v_add_co_u32_e32 v0, vcc, 0x1000, v0
	s_cmp_lg_u32 s35, 0
	s_nop 0
	v_addc_co_u32_e32 v1, vcc, 0, v1, vcc
	global_load_dwordx2 v[32:33], v[0:1], off offset:576
	s_cselect_b64 s[16:17], -1, 0
	s_and_b64 s[18:19], s[4:5], s[16:17]
	s_and_saveexec_b64 s[16:17], s[18:19]
	s_cbranch_execz .LBB0_652
	s_sub_i32 s21, s20, 32
	s_sub_i32 vcc_lo, 0x7e0, s21
	s_cmp_lg_u64 s[0:1], 0
	s_cselect_b32 vcc_lo, s21, vcc_lo
	s_add_i32 vcc_lo, vcc_lo, s46
	s_lshl_b32 vcc_lo, vcc_lo, 11
	s_add_u32 s18, s68, vcc_lo
	s_addc_u32 s19, s69, 0
	v_add_u32_e32 v160, v45, v166
	v_add_u32_e32 v161, v44, v166
	ds_read_b64 v[162:163], v160
	ds_read_b64 v[164:165], v161
	s_waitcnt lgkmcnt(1)
	global_store_dwordx2 v167, v[162:163], s[18:19]
	s_waitcnt lgkmcnt(0)
	global_store_dwordx2 v168, v[164:165], s[18:19]
	s_or_b64 exec, exec, s[16:17]
	s_waitcnt vmcnt(8)
	s_branch .Llw_join_647a
.LBB0_652:
	s_or_b64 exec, exec, s[16:17]
	s_waitcnt vmcnt(6)
.Llw_join_647a:
	v_lshlrev_b32_e32 v2, 16, v59
	v_mul_f32_e32 v0, 0xbfb8aa3b, v2
	v_exp_f32_e32 v0, v0
	v_and_b32_e32 v59, 0xffff0000, v59
	v_mul_f32_e32 v1, 0xbfb8aa3b, v59
	v_exp_f32_e32 v1, v1
	v_add_f32_e32 v0, 1.0, v0
	v_rcp_f32_e32 v0, v0
	v_mul_f32_e32 v2, 0x3fb8aa3b, v2
	v_add_f32_e32 v1, 1.0, v1
	v_rcp_f32_e32 v1, v1
	v_fma_f32 v0, v24, v0, v20
	v_max_f32_e32 v0, 0x1e3ce508, v0
	v_cmp_gt_f32_e32 vcc, s26, v0
	v_fma_f32 v1, v25, v1, v21
	v_max_f32_e32 v1, 0x1e3ce508, v1
	v_cndmask_b32_e64 v62, 0, 32, vcc
	v_ldexp_f32 v0, v0, v62
	v_log_f32_e32 v0, v0
	v_cmp_gt_f32_e64 s[16:17], s26, v1
	v_exp_f32_e32 v2, v2
	v_mul_f32_e32 v59, 0x3fb8aa3b, v59
	v_cndmask_b32_e64 v62, 0, 32, s[16:17]
	v_mul_f32_e32 v63, 0x3f317217, v0
	v_ldexp_f32 v1, v1, v62
	v_fma_f32 v63, v0, s31, -v63
	v_log_f32_e32 v1, v1
	v_fmac_f32_e32 v63, 0x3377d1cf, v0
	v_fmac_f32_e32 v63, 0x3f317217, v0
	v_cmp_lt_f32_e64 s[18:19], |v0|, s27
	v_cndmask_b32_e32 v62, 0, v157, vcc
	v_exp_f32_e32 v59, v59
	v_cndmask_b32_e64 v0, v0, v63, s[18:19]
	v_sub_f32_e32 v0, v0, v62
	v_mul_f32_e32 v62, 0x3f317217, v1
	v_fma_f32 v62, v1, s31, -v62
	v_fmac_f32_e32 v62, 0x3377d1cf, v1
	v_fmac_f32_e32 v62, 0x3f317217, v1
	v_cmp_lt_f32_e64 vcc, |v1|, s27
	v_add_f32_e32 v2, 1.0, v2
	v_rcp_f32_e32 v64, v2
	v_cndmask_b32_e32 v1, v1, v62, vcc
	v_cndmask_b32_e64 v62, 0, v157, s[16:17]
	v_sub_f32_e32 v1, v1, v62
	v_lshlrev_b32_e32 v62, 16, v57
	v_add_f32_e32 v2, 1.0, v59
	v_and_b32_e32 v63, 0xffff0000, v57
	v_rcp_f32_e32 v65, v2
	v_mul_f32_e32 v2, 0xbfb8aa3b, v62
	v_exp_f32_e32 v2, v2
	v_mul_f32_e32 v57, 0xbfb8aa3b, v63
	v_exp_f32_e32 v57, v57
	v_add_f32_dpp v0, v0, v0 row_shr:1 row_mask:0xf bank_mask:0xf bound_ctrl:1
	v_add_f32_dpp v1, v1, v1 row_shr:1 row_mask:0xf bank_mask:0xf bound_ctrl:1
	v_add_f32_e32 v2, 1.0, v2
	v_add_f32_dpp v0, v0, v0 row_shr:2 row_mask:0xf bank_mask:0xf bound_ctrl:1
	v_add_f32_dpp v1, v1, v1 row_shr:2 row_mask:0xf bank_mask:0xf bound_ctrl:1
	v_rcp_f32_e32 v66, v2
	v_add_f32_e32 v2, 1.0, v57
	v_add_f32_dpp v0, v0, v0 row_shr:4 row_mask:0xf bank_mask:0xf bound_ctrl:1
	v_add_f32_dpp v1, v1, v1 row_shr:4 row_mask:0xf bank_mask:0xf bound_ctrl:1
	v_rcp_f32_e32 v67, v2
	v_add_f32_dpp v70, v0, v0 row_shr:8 row_mask:0xf bank_mask:0xf bound_ctrl:1
	v_add_f32_dpp v71, v1, v1 row_shr:8 row_mask:0xf bank_mask:0xf bound_ctrl:1
	v_mul_f32_e32 v59, 0x3fb8aa3b, v70
	v_mul_f32_e32 v2, 0x3fb8aa3b, v71
	v_exp_f32_e32 v68, v59
	v_exp_f32_e32 v69, v2
	v_mul_f32_e32 v2, 0xbfb8aa3b, v70
	v_pk_mul_f32 v[62:63], v[66:67], v[62:63]
	v_exp_f32_e32 v66, v2
	v_mul_f32_e32 v2, 0xbfb8aa3b, v71
	v_exp_f32_e32 v67, v2
	ds_bpermute_b32 v0, v38, v70
	v_pk_mul_f32 v[62:63], v[62:63], v[68:69]
	ds_bpermute_b32 v1, v38, v71
	v_cvt_pk_bf16_f32 v2, v62, v63
	v_pk_mul_f32 v[62:63], v[24:25], v[64:65]
	s_nop 0
	v_pk_mul_f32 v[64:65], v[62:63], v[66:67]
	s_nop 0
	v_cvt_pk_bf16_f32 v57, v64, v65
	ds_write2st64_b32 v39, v2, v57 offset0:94 offset1:103
	s_waitcnt lgkmcnt(2)
	v_sub_f32_e32 v2, v0, v70
	v_mul_f32_e32 v2, 0x3fb8aa3b, v2
	v_exp_f32_e32 v2, v2
	s_waitcnt lgkmcnt(1)
	v_sub_f32_e32 v57, v1, v71
	v_mul_f32_e32 v57, 0x3fb8aa3b, v57
	v_exp_f32_e32 v57, v57
	v_mul_f32_e32 v2, v62, v2
	v_cvt_pk_bf16_f32 v2, v2, s0
	ds_write_b16 v40, v2 offset:28672
	v_mul_f32_e32 v2, v63, v57
	v_cvt_pk_bf16_f32 v2, v2, s0
	ds_write_b16 v40, v2 offset:28704
	s_and_saveexec_b64 s[16:17], s[14:15]
	s_cbranch_execz .LBB0_654
	v_mul_f32_e32 v1, 0x3fb8aa3b, v1
	v_mul_f32_e32 v0, 0x3fb8aa3b, v0
	v_exp_f32_e32 v1, v1
	v_exp_f32_e32 v0, v0
	ds_write_b64 v41, v[0:1] offset:35840

; template <int MODE>
; __device__ void scan_unit(int swave, const Params& p, int j, int b, int h, int dir, char* shm) {
;     ...
;   auto compute = [&](const char* buf, bf16_t* obuf) {
;     const bf16_t* qin = (const bf16_t*)buf; const bf16_t* ktil = (const bf16_t*)(buf + OFF_KT); const bf16_t* koutT = (const bf16_t*)(buf + OFF_KO);
;     const bf16_t* vT = (const bf16_t*)(buf + OFF_VT); const float* dec = (const float*)(buf + OFF_DEC);
;     bf16x8 Asc = {0, 0, 0, 0, 0, 0, 0, 0};
;     if (KS == 1 || wk == 0) {
;       f32x4 sc = {0.f, 0.f, 0.f, 0.f};
; #pragma unroll
;       for (int m = 0; m < DK / 32; ++m) {
;         const bf16x8 a = *(const bf16x8*)(ktil + r * QS + m * 32 + q4 * 8);
;         const bf16x8 bb = *(const bf16x8*)(qin + r * QS + m * 32 + q4 * 8);
;         sc = __builtin_amdgcn_mfma_f32_16x16x32_bf16(a, bb, sc, 0, 0, 0);
;       }
;       {
;         const unsigned p01 = pk2(q4 * 4 + 0 > r ? 0.f : sc[0], q4 * 4 + 1 > r ? 0.f : sc[1]);
;         const unsigned p23 = pk2(q4 * 4 + 2 > r ? 0.f : sc[2], q4 * 4 + 3 > r ? 0.f : sc[3]);
;         Asc[0] = (short)(p01 & 0xffff); Asc[1] = (short)(p01 >> 16); Asc[2] = (short)(p23 & 0xffff); Asc[3] = (short)(p23 >> 16);
;       }
;     }
;     bf16x8 Bv[NVT];
; #pragma unroll
;     for (int t = 0; t < NVT; ++t) {
;       const uint2 vv = *(const uint2*)(vT + ((vt0 + t) * 16 + r) * VS + q4 * 4);
;       Bv[t] = (bf16x8){(short)(vv.x & 0xffff), (short)(vv.x >> 16), (short)(vv.y & 0xffff), (short)(vv.y >> 16), 0, 0, 0, 0};
;     }
;     bf16x8 Aq[2];
; #pragma unroll
;     for (int m = 0; m < 2; ++m) {
;       const uint2 lo = *(const uint2*)(qin + r * QS + slab + (2 * m) * 16 + q4 * 4);
;       const uint2 hi = *(const uint2*)(qin + r * QS + slab + (2 * m + 1) * 16 + q4 * 4);
;       Aq[m] = (bf16x8){(short)(lo.x & 0xffff), (short)(lo.x >> 16), (short)(lo.y & 0xffff), (short)(lo.y >> 16),
;                        (short)(hi.x & 0xffff), (short)(hi.x >> 16), (short)(hi.y & 0xffff), (short)(hi.y >> 16)};
;     }
;     f32x4 o[NVT];
; #pragma unroll
;     for (int t = 0; t < NVT; ++t) {
;       o[t] = (f32x4){0.f, 0.f, 0.f, 0.f};
;       if (KS == 1 || wk == 0) o[t] = __builtin_amdgcn_mfma_f32_16x16x32_bf16(Asc, Bv[t], o[t], 0, 0, 0);
;     }
; #pragma unroll
;     for (int m = 0; m < 2; ++m)
; #pragma unroll
;       for (int t = 0; t < NVT; ++t) {
;         const f32x4 s0 = S[2 * m][t], s1 = S[2 * m + 1][t];
.LBB0_656:
	s_or_b64 exec, exec, s[16:17]
	ds_write_b16 v42, v28 offset:42752
	ds_write_b16_d16_hi v42, v28 offset:42792
	ds_write_b16 v42, v29 offset:42832
	ds_write_b16_d16_hi v42, v29 offset:42872
	ds_read_b128 v[28:31], v46 offset:2304
	ds_read_b128 v[62:65], v46
	ds_read_b128 v[66:69], v46 offset:2368
	ds_read_b128 v[70:73], v46 offset:64
	v_mov_b32_e32 v2, v3
	v_add_u32_e32 v54, 0x2800, v53
	s_waitcnt lgkmcnt(2)
	v_mfma_f32_16x16x32_bf16 v[28:31], v[28:31], v[62:65], 0
	ds_read_b64 v[62:63], v47 offset:6656
	ds_read2_b64 v[74:77], v53 offset1:4
	ds_read2_b64 v[78:81], v53 offset0:8 offset1:12
	v_mov_b32_e32 v64, v3
	v_mov_b32_e32 v65, v3
	s_waitcnt lgkmcnt(3)
	v_mfma_f32_16x16x32_bf16 v[28:31], v[66:69], v[70:73], v[28:31]
	s_waitcnt lgkmcnt(1)
	v_bfi_b32 v76, s30, v76, v76
	s_waitcnt lgkmcnt(0)
	v_bfi_b32 v80, s30, v80, v80
	v_cvt_pk_bf16_f32 v66, v16, v17
	v_cvt_pk_bf16_f32 v67, v18, v19
	v_cvt_pk_bf16_f32 v68, v12, v13
	s_nop 0
	v_cndmask_b32_e64 v0, v28, 0, s[6:7]
	v_cndmask_b32_e64 v1, 0, v29, s[8:9]
	v_cndmask_b32_e64 v28, v30, 0, s[10:11]
	v_cndmask_b32_e64 v29, v31, 0, s[12:13]
	v_cvt_pk_bf16_f32 v0, v0, v1
	v_cvt_pk_bf16_f32 v1, v28, v29
	v_cvt_pk_bf16_f32 v69, v14, v15
	s_nop 0
	v_mfma_f32_16x16x32_bf16 v[28:31], v[0:3], v[62:65], 0
	v_mfma_f32_16x16x32_bf16 v[28:31], v[74:77], v[66:69], v[28:31]
	v_cvt_pk_bf16_f32 v66, v8, v9
	v_cvt_pk_bf16_f32 v67, v10, v11
	v_cvt_pk_bf16_f32 v68, v4, v5
	v_cvt_pk_bf16_f32 v69, v6, v7
	s_nop 1
	v_mfma_f32_16x16x32_bf16 v[28:31], v[78:81], v[66:69], v[28:31]
	s_nop 7
	v_cvt_pk_bf16_f32 v0, v28, s0
	v_cvt_pk_bf16_f32 v1, v29, s0
	ds_write_b16 v48, v0 offset:48128
	ds_write_b16 v48, v1 offset:48392
	v_cvt_pk_bf16_f32 v0, v30, s0
	ds_write_b16 v48, v0 offset:48656
	v_cvt_pk_bf16_f32 v0, v31, s0
	ds_write_b16 v48, v0 offset:48920
	ds_read2st64_b64 v[28:31], v49 offset0:9 offset1:10
	ds_read2st64_b64 v[66:69], v49 offset0:11 offset1:12
	ds_read_b128 v[70:73], v50 offset:11776
	ds_read_b128 v[74:77], v50 offset:11840
	s_waitcnt lgkmcnt(3)
	s_waitcnt lgkmcnt(1)
	v_pk_mul_f32 v[18:19], v[18:19], v[72:73]
	v_pk_mul_f32 v[16:17], v[16:17], v[70:71]
	s_waitcnt lgkmcnt(0)
	v_pk_mul_f32 v[14:15], v[14:15], v[76:77]
	v_pk_mul_f32 v[12:13], v[12:13], v[74:75]
	v_mfma_f32_16x16x16_bf16 v[16:19], v[28:29], v[62:63], v[16:19]
	v_mov_b32_e32 v0, v30
	v_mov_b32_e32 v1, v31
	ds_read_b128 v[28:31], v50 offset:11904
	ds_read_b128 v[70:73], v50 offset:11968
	v_mfma_f32_16x16x16_bf16 v[12:15], v[0:1], v[62:63], v[12:15]
	s_waitcnt lgkmcnt(1)
	v_pk_mul_f32 v[10:11], v[10:11], v[30:31]
	v_pk_mul_f32 v[8:9], v[8:9], v[28:29]
	v_cvt_pk_bf16_f32 v74, v16, v17
	v_cvt_pk_bf16_f32 v75, v18, v19
	v_mfma_f32_16x16x16_bf16 v[28:31], v[66:67], v[62:63], v[8:11]
	s_nop 1
	v_cvt_pk_bf16_f32 v76, v12, v13
	ds_read_b128 v[8:11], v46 offset:14336
	s_waitcnt lgkmcnt(1)
	v_pk_mul_f32 v[6:7], v[6:7], v[72:73]
	v_pk_mul_f32 v[4:5], v[4:5], v[70:71]
	v_cvt_pk_bf16_f32 v77, v14, v15
	s_nop 0
	v_mfma_f32_16x16x16_bf16 v[4:7], v[68:69], v[62:63], v[4:7]
	ds_read_b128 v[62:65], v46 offset:14400
	ds_read_b128 v[66:69], v46 offset:12032
	ds_read_b128 v[70:73], v46 offset:12096
	s_waitcnt lgkmcnt(1)
	v_mfma_f32_16x16x32_bf16 v[8:11], v[8:11], v[66:69], 0
	v_mov_b32_e32 v68, v3
	v_mov_b32_e32 v69, v3
	s_waitcnt lgkmcnt(0)
	v_mfma_f32_16x16x32_bf16 v[8:11], v[62:65], v[70:73], v[8:11]
	s_nop 7
	v_cndmask_b32_e64 v0, v8, 0, s[6:7]
	v_cndmask_b32_e64 v1, 0, v9, s[8:9]
	v_cvt_pk_bf16_f32 v0, v0, v1
	v_cndmask_b32_e64 v1, v10, 0, s[10:11]
	v_cndmask_b32_e64 v2, v11, 0, s[12:13]
	ds_read2_b64 v[8:11], v54 offset0:224 offset1:228
	ds_read2_b64 v[62:65], v54 offset0:232 offset1:236
	v_cvt_pk_bf16_f32 v1, v1, v2
	ds_read_b64 v[66:67], v47 offset:18688
	v_mov_b32_e32 v2, v3
	s_waitcnt lgkmcnt(2)
	v_bfi_b32 v10, s30, v10, v10
	s_waitcnt lgkmcnt(1)
	v_bfi_b32 v64, s30, v64, v64
	s_waitcnt lgkmcnt(0)
	v_mfma_f32_16x16x32_bf16 v[70:73], v[0:3], v[66:69], 0
	v_mfma_f32_16x16x32_bf16 v[8:11], v[8:11], v[74:77], v[70:73]
	s_nop 6
	v_cvt_pk_bf16_f32 v70, v28, v29
	v_cvt_pk_bf16_f32 v71, v30, v31
	v_cvt_pk_bf16_f32 v72, v4, v5
	v_cvt_pk_bf16_f32 v73, v6, v7
	s_nop 1
	v_mfma_f32_16x16x32_bf16 v[8:11], v[62:65], v[70:73], v[8:11]
	v_add_u32_e32 v62, 0x100, v49
	s_nop 6
	v_cvt_pk_bf16_f32 v0, v8, s0
	ds_write_b16 v48, v0 offset:52352
	v_cvt_pk_bf16_f32 v0, v9, s0
	ds_write_b16 v48, v0 offset:52616
	v_cvt_pk_bf16_f32 v0, v10, s0
	ds_write_b16 v48, v0 offset:52880
	v_cvt_pk_bf16_f32 v0, v11, s0
	ds_write_b16 v48, v0 offset:53144
	ds_read2st64_b64 v[70:73], v62 offset0:32 offset1:33
	ds_read2st64_b64 v[74:77], v62 offset0:34 offset1:35
	ds_read_b128 v[8:11], v50 offset:23808
	ds_read_b128 v[78:81], v50 offset:23872
	s_waitcnt lgkmcnt(3)
	s_waitcnt lgkmcnt(1)
	v_pk_mul_f32 v[10:11], v[18:19], v[10:11]
	v_pk_mul_f32 v[8:9], v[16:17], v[8:9]
	s_waitcnt lgkmcnt(0)
	v_pk_mul_f32 v[14:15], v[14:15], v[80:81]
	v_pk_mul_f32 v[12:13], v[12:13], v[78:79]
	v_mfma_f32_16x16x16_bf16 v[8:11], v[70:71], v[66:67], v[8:11]
	v_mov_b32_e32 v0, v72
	v_mov_b32_e32 v1, v73
	ds_read_b128 v[16:19], v50 offset:23936
	ds_read_b128 v[70:73], v50 offset:24000
	v_mfma_f32_16x16x16_bf16 v[12:15], v[0:1], v[66:67], v[12:15]
	s_waitcnt lgkmcnt(1)
	v_pk_mul_f32 v[18:19], v[30:31], v[18:19]
	v_pk_mul_f32 v[16:17], v[28:29], v[16:17]
	s_waitcnt lgkmcnt(0)
	v_pk_mul_f32 v[6:7], v[6:7], v[72:73]
	v_pk_mul_f32 v[4:5], v[4:5], v[70:71]
	v_mfma_f32_16x16x16_bf16 v[16:19], v[74:75], v[66:67], v[16:19]
	s_waitcnt lgkmcnt(0)
	s_barrier
; __device__ __forceinline__ unsigned pk2(float lo, float hi) { f32x2_t v = {lo, hi}; bf16x2_t b = __builtin_convertvector(v, bf16x2_t); return __builtin_bit_cast(unsigned, b); }
; __device__ __forceinline__ bf16_t f2bf(float f) { return (bf16_t)(pk2(f, 0.f) & 0xffffu); }
; __device__ __forceinline__ float lo_bf(unsigned u) { return __uint_as_float(u << 16); }
; __device__ __forceinline__ float hi_bf(unsigned u) { return __uint_as_float(u & 0xffff0000u); }
; __device__ __forceinline__ float sigmoidf_(float x) { return __builtin_amdgcn_rcpf(1.f + __expf(-x)); }
; __device__ __forceinline__ float siluf_(float x) { return x * __builtin_amdgcn_rcpf(1.f + __expf(-x)); }
; template <int MODE>
; __device__ void scan_unit(int swave, const Params& p, int j, int b, int h, int dir, char* shm) {
;     ...
;       } else {
;         const float f0 = lbv0 + (1.f - lbv0) * sigmoidf_(lo_bf(R.k)), f1 = lbv1 + (1.f - lbv1) * sigmoidf_(hi_bf(R.k));
;         g0 = __logf(fmaxf(f0, 1e-20f)); g1 = __logf(fmaxf(f1, 1e-20f));
;       }
;       float s0, s1;
;       const float cum0 = row_scan(g0, s0), cum1 = row_scan(g1, s1);
;       float q0, q1, k0, k1;
;       if (MODE == 0) { q0 = lo_bf(R.q); q1 = hi_bf(R.q); k0 = lo_bf(R.k) * 0.125f; k1 = hi_bf(R.k) * 0.125f; }
;       else { q0 = siluf_(lo_bf(R.q)); q1 = siluf_(hi_bf(R.q)); k0 = (1.f - lbv0) * sigmoidf_(-lo_bf(R.k)); k1 = (1.f - lbv1) * sigmoidf_(-hi_bf(R.k)); }
;       *(unsigned*)(qin + ti * QS + dp) = pk2(q0 * __expf(cum0), q1 * __expf(cum1));
;       *(unsigned*)(ktil + ti * QS + dp) = pk2(k0 * __expf(-cum0), k1 * __expf(-cum1));
;       koutT[dp * 16 + ti] = f2bf(k0 * __expf(s0 - cum0));
;       koutT[(dp + 1) * 16 + ti] = f2bf(k1 * __expf(s1 - cum1));
;       if (ti == 0) *(float2*)(dec + dp) = make_float2(__expf(s0), __expf(s1));
;     ...
;   auto body = [&](int it, Raw& c0, Raw& c1, Raw& n0, Raw& n1) {
;     touch(c0); touch(c1);
;     __builtin_amdgcn_sched_barrier(0);
;     const int cA = 2 * it + 4 < NCH ? 2 * it + 4 : NCH - 2;
;     load_raw(cA, n0); load_raw(cA + 1, n1);
;     if (it > 0) { ostore(2 * it - 2, obp((it - 1) & 1, 0)); ostore(2 * it - 1, obp((it - 1) & 1, 1)); }
;     stage2(c0, bufp((it + 1) & 1, 0), 0); stage2(c1, bufp((it + 1) & 1, 1), 0);
	v_mfma_f32_16x16x16_bf16 v[4:7], v[76:77], v[66:67], v[4:7]
	s_add_i32 s16, s20, 0x60
	s_and_b64 s[2:3], s[2:3], exec
	s_cselect_b32 s2, s16, 0x7e0
	v_or_b32_e32 v2, s2, v37
	v_sub_u32_e32 v0, 0x7ff, v2
	v_cndmask_b32_e64 v0, v0, v2, s[0:1]
	v_or_b32_e32 v2, 16, v2
	v_ashrrev_i32_e32 v1, 31, v0
	v_sub_u32_e32 v57, 0x7ff, v2
	v_lshl_add_u64 v[0:1], s[46:47], 0, v[0:1]
	v_mov_b64_e32 v[28:29], s[48:49]
	v_cndmask_b32_e64 v64, v57, v2, s[0:1]
	v_mad_u64_u32 v[30:31], s[2:3], v0, s53, v[28:29]
	v_ashrrev_i32_e32 v65, 31, v64
	v_mad_i32_i24 v31, v1, s53, v31
	s_mov_b32 s71, s95
	v_lshl_add_u64 v[64:65], s[46:47], 0, v[64:65]
	v_lshl_add_u64 v[0:1], v[30:31], 0, s[50:51]
	v_lshl_add_u64 v[54:55], v[30:31], 0, s[94:95]
	v_lshl_add_u64 v[30:31], v[30:31], 0, s[70:71]
	v_mad_u64_u32 v[28:29], s[2:3], v64, s53, v[28:29]
	v_lshl_add_u64 v[30:31], v[30:31], 0, v[26:27]
	v_mad_i32_i24 v29, v65, s53, v29
	v_lshl_add_u64 v[54:55], v[54:55], 0, s[50:51]
	v_add_co_u32_e32 v30, vcc, s62, v30
	v_lshl_add_u64 v[66:67], v[28:29], 0, s[94:95]
	v_lshl_add_u64 v[0:1], v[0:1], 0, v[22:23]
	v_lshl_add_u64 v[54:55], v[54:55], 0, v[22:23]
	v_addc_co_u32_e32 v31, vcc, 0, v31, vcc
	v_lshl_add_u64 v[64:65], v[28:29], 0, s[50:51]
	v_lshl_add_u64 v[66:67], v[66:67], 0, s[50:51]
	v_lshl_add_u64 v[64:65], v[64:65], 0, v[22:23]
	v_lshl_add_u64 v[66:67], v[66:67], 0, v[22:23]
	global_load_dword v57, v[0:1], off offset:3136
	global_load_dword v59, v[54:55], off
	s_nop 0
	global_load_dwordx2 v[30:31], v[30:31], off offset:576
	s_nop 0
	global_load_dword v54, v[64:65], off offset:3136
	global_load_dword v55, v[66:67], off
	v_lshl_add_u64 v[0:1], v[28:29], 0, s[70:71]
	v_lshl_add_u64 v[0:1], v[0:1], 0, v[26:27]
	v_add_co_u32_e32 v0, vcc, 0x1000, v0
	s_nop 1
	v_addc_co_u32_e32 v1, vcc, 0, v1, vcc
	global_load_dwordx2 v[28:29], v[0:1], off offset:576
	s_and_saveexec_b64 s[2:3], s[4:5]
	s_cbranch_execz .LBB0_661
	s_sub_i32 vcc_lo, 0x7e0, s20
	s_cmp_lg_u64 s[0:1], 0
	s_cselect_b32 vcc_lo, s20, vcc_lo
	s_add_i32 vcc_lo, vcc_lo, s46
	s_lshl_b32 vcc_lo, vcc_lo, 11
	s_add_u32 s16, s68, vcc_lo
	s_addc_u32 s17, s69, 0
	v_add_u32_e32 v160, v51, v166
	v_add_u32_e32 v161, v52, v166
	ds_read_b64 v[162:163], v160
	ds_read_b64 v[164:165], v161
	s_waitcnt lgkmcnt(1)
	global_store_dwordx2 v167, v[162:163], s[16:17]
	s_waitcnt lgkmcnt(0)
	global_store_dwordx2 v168, v[164:165], s[16:17]
	s_or_b64 exec, exec, s[2:3]
	s_waitcnt vmcnt(8)
	s_branch .Llw_join_647b
.LBB0_661:
	s_or_b64 exec, exec, s[2:3]
	s_waitcnt vmcnt(6)
.Llw_join_647b:
	v_lshlrev_b32_e32 v2, 16, v61
	v_mul_f32_e32 v0, 0xbfb8aa3b, v2
	v_exp_f32_e32 v0, v0
	v_and_b32_e32 v61, 0xffff0000, v61
	v_mul_f32_e32 v1, 0xbfb8aa3b, v61
	v_exp_f32_e32 v1, v1
	v_add_f32_e32 v0, 1.0, v0
	v_rcp_f32_e32 v0, v0
	v_mul_f32_e32 v2, 0x3fb8aa3b, v2
	v_add_f32_e32 v1, 1.0, v1
	v_rcp_f32_e32 v1, v1
	v_fma_f32 v0, v24, v0, v20
	v_max_f32_e32 v0, 0x1e3ce508, v0
	v_cmp_gt_f32_e32 vcc, s26, v0
	v_fma_f32 v1, v25, v1, v21
	v_max_f32_e32 v1, 0x1e3ce508, v1
	v_cndmask_b32_e64 v63, 0, 32, vcc
	v_ldexp_f32 v0, v0, v63
	v_log_f32_e32 v0, v0
	v_cmp_gt_f32_e64 s[16:17], s26, v1
	v_exp_f32_e32 v2, v2
	v_mul_f32_e32 v61, 0x3fb8aa3b, v61
	v_cndmask_b32_e64 v63, 0, 32, s[16:17]
	v_mul_f32_e32 v64, 0x3f317217, v0
	v_ldexp_f32 v1, v1, v63
	v_fma_f32 v64, v0, s31, -v64
	v_log_f32_e32 v1, v1
	v_exp_f32_e32 v61, v61
	v_fmac_f32_e32 v64, 0x3377d1cf, v0
	v_fmac_f32_e32 v64, 0x3f317217, v0
	v_cmp_lt_f32_e64 s[18:19], |v0|, s27
	v_cndmask_b32_e32 v63, 0, v157, vcc
	v_add_f32_e32 v2, 1.0, v2
	v_cndmask_b32_e64 v0, v0, v64, s[18:19]
	v_sub_f32_e32 v0, v0, v63
	v_mul_f32_e32 v63, 0x3f317217, v1
	v_lshlrev_b32_e32 v64, 16, v60
	v_and_b32_e32 v65, 0xffff0000, v60
	v_rcp_f32_e32 v60, v2
	v_add_f32_e32 v2, 1.0, v61
	v_fma_f32 v63, v1, s31, -v63
	v_rcp_f32_e32 v61, v2
	v_mul_f32_e32 v2, 0xbfb8aa3b, v64
	v_fmac_f32_e32 v63, 0x3377d1cf, v1
	v_exp_f32_e32 v2, v2
	v_mul_f32_e32 v66, 0xbfb8aa3b, v65
	v_fmac_f32_e32 v63, 0x3f317217, v1
	v_cmp_lt_f32_e64 vcc, |v1|, s27
	v_exp_f32_e32 v67, v66
	v_add_f32_e32 v2, 1.0, v2
	v_cndmask_b32_e32 v1, v1, v63, vcc
	v_cndmask_b32_e64 v63, 0, v157, s[16:17]
	v_sub_f32_e32 v1, v1, v63
	v_add_f32_dpp v0, v0, v0 row_shr:1 row_mask:0xf bank_mask:0xf bound_ctrl:1
	v_rcp_f32_e32 v66, v2
	v_add_f32_dpp v1, v1, v1 row_shr:1 row_mask:0xf bank_mask:0xf bound_ctrl:1
	v_add_f32_e32 v2, 1.0, v67
	v_add_f32_dpp v0, v0, v0 row_shr:2 row_mask:0xf bank_mask:0xf bound_ctrl:1
	v_add_f32_dpp v1, v1, v1 row_shr:2 row_mask:0xf bank_mask:0xf bound_ctrl:1
	v_rcp_f32_e32 v67, v2
	v_add_f32_dpp v0, v0, v0 row_shr:4 row_mask:0xf bank_mask:0xf bound_ctrl:1
	v_add_f32_dpp v1, v1, v1 row_shr:4 row_mask:0xf bank_mask:0xf bound_ctrl:1
	v_pk_mul_f32 v[60:61], v[24:25], v[60:61]
	v_add_f32_dpp v63, v0, v0 row_shr:8 row_mask:0xf bank_mask:0xf bound_ctrl:1
	v_add_f32_dpp v70, v1, v1 row_shr:8 row_mask:0xf bank_mask:0xf bound_ctrl:1
	v_mul_f32_e32 v2, 0x3fb8aa3b, v70
	v_mul_f32_e32 v68, 0x3fb8aa3b, v63
	v_exp_f32_e32 v69, v2
	v_mul_f32_e32 v2, 0xbfb8aa3b, v63
	v_exp_f32_e32 v68, v68
	v_pk_mul_f32 v[64:65], v[66:67], v[64:65]
	v_exp_f32_e32 v66, v2
	v_mul_f32_e32 v2, 0xbfb8aa3b, v70
	v_exp_f32_e32 v67, v2
	ds_bpermute_b32 v0, v38, v63
	ds_bpermute_b32 v1, v38, v70
	v_pk_mul_f32 v[64:65], v[64:65], v[68:69]
	s_nop 0
	v_cvt_pk_bf16_f32 v2, v64, v65
	v_pk_mul_f32 v[64:65], v[60:61], v[66:67]
	s_nop 0
	v_cvt_pk_bf16_f32 v64, v64, v65
	ds_write2st64_b32 v39, v2, v64 offset1:9
	s_waitcnt lgkmcnt(2)
	v_sub_f32_e32 v2, v0, v63
	v_mul_f32_e32 v2, 0x3fb8aa3b, v2
	v_exp_f32_e32 v2, v2
	s_waitcnt lgkmcnt(1)
	v_sub_f32_e32 v63, v1, v70
	v_mul_f32_e32 v63, 0x3fb8aa3b, v63
	v_exp_f32_e32 v63, v63
	v_mul_f32_e32 v2, v60, v2
	v_cvt_pk_bf16_f32 v2, v2, s0
	ds_write_b16 v40, v2 offset:4608
	v_mul_f32_e32 v2, v61, v63
	v_cvt_pk_bf16_f32 v2, v2, s0
	ds_write_b16 v40, v2 offset:4640
	s_and_saveexec_b64 s[2:3], s[14:15]
	s_cbranch_execz .LBB0_663
	v_mul_f32_e32 v1, 0x3fb8aa3b, v1
	v_mul_f32_e32 v0, 0x3fb8aa3b, v0
	v_exp_f32_e32 v1, v1
	v_exp_f32_e32 v0, v0
	ds_write_b64 v41, v[0:1] offset:11776

; __device__ __forceinline__ unsigned pk2(float lo, float hi) { f32x2_t v = {lo, hi}; bf16x2_t b = __builtin_convertvector(v, bf16x2_t); return __builtin_bit_cast(unsigned, b); }
; __device__ __forceinline__ float lo_bf(unsigned u) { return __uint_as_float(u << 16); }
; __device__ __forceinline__ float hi_bf(unsigned u) { return __uint_as_float(u & 0xffff0000u); }
; template <int MODE>
; __device__ void scan_unit(int swave, const Params& p, int j, int b, int h, int dir, char* shm) {
;     ...
;   auto load_raw = [&](int c, Raw& R) {
;     const int tok = tokof(c, ti);
;     const bf16_t* row = P + (rowbase + tok) * LDP;
;     if (MODE == 0) {
;       R.q = *(const unsigned*)(row + E_GQ + h * 64 + dp); R.k = *(const unsigned*)(row + E_GK + h * 64 + dp);
;       const uint4* lrp = (const uint4*)(row + (dir ? E_GLB : E_GLF));
;       R.lr0 = lrp[0]; R.lr1 = lrp[1];
;       R.v = *(const uint2*)(row + E_GV + h * 128 + vg * 4);
;     } else if (MODE == 1) {
;       R.q = *(const unsigned*)(row + E_HQ + h * 64 + dp); R.k = *(const unsigned*)(row + (dir ? E_HZB : E_HZF) + h * 64 + dp);
;       R.v = *(const uint2*)(row + E_HI + h * 128 + vg * 4);
;     } else {
;       R.q = *(const unsigned*)(row + O_RQ + h * 128 + dp); R.q2 = *(const unsigned*)(row + O_RQ + h * 128 + 64 + dp);
;       R.k = *(const unsigned*)(row + O_RK + h * 128 + dp); R.k2 = *(const unsigned*)(row + O_RK + h * 128 + 64 + dp);
;       R.cs = *(const float4*)(rope + tok * 64 + dp);
;       const unsigned* vp = (const unsigned*)(row + O_RV + h * 192 + vg * 6);
;       R.v30 = vp[0]; R.v31 = vp[1]; R.v32 = vp[2];
;     }
;   };
;     ...
;   auto ostore = [&](int c, const bf16_t* obuf) {
;     for (int idx = tid; idx < 16 * DV / 4; idx += 512) {
;       const int i = idx / (DV / 4), cc = (idx % (DV / 4)) * 4;
;       uint2 o = *(const uint2*)(obuf + i * OS + cc);
;       if (KS == 2) {
;         const uint2 o2 = *(const uint2*)(obuf + (16 + i) * OS + cc);
;         o.x = pk2(lo_bf(o.x) + lo_bf(o2.x), hi_bf(o.x) + hi_bf(o2.x)); o.y = pk2(lo_bf(o.y) + lo_bf(o2.y), hi_bf(o.y) + hi_bf(o2.y));
;       }
;       *(uint2*)(O + (rowbase + tokof(c, i)) * OLD + cc) = o;
;     }
.LBB0_677:
	s_cmp_gt_u32 s35, 61
	s_cselect_b64 s[72:73], -1, 0
	s_lshl_b32 s28, s35, 5
	s_add_i32 s20, s28, 64
	s_cmp_lt_u32 s35, 62
	s_cselect_b64 s[2:3], -1, 0
	s_and_b64 s[16:17], s[2:3], exec
	s_cselect_b32 s16, s20, 0x7e0
	v_or_b32_e32 v2, s16, v99
	v_sub_u32_e32 v0, 0x7ff, v2
	v_cndmask_b32_e64 v0, v0, v2, s[0:1]
	v_ashrrev_i32_e32 v1, 31, v0
	v_lshl_add_u64 v[0:1], s[18:19], 0, v[0:1]
	v_mov_b64_e32 v[20:21], s[46:47]
	v_mad_u64_u32 v[22:23], s[16:17], v0, s53, v[20:21]
	v_mad_i32_i24 v23, v1, s53, v23
	v_lshl_add_u64 v[0:1], v[22:23], 0, s[94:95]
	v_lshl_add_u64 v[0:1], v[0:1], 0, v[82:83]
	v_lshl_add_u64 v[24:25], v[22:23], 0, s[70:71]
	global_load_dword v123, v[0:1], off
	global_load_dword v122, v[0:1], off offset:512
	global_load_dwordx4 v[32:35], v[24:25], off
	v_lshl_add_u64 v[0:1], v[22:23], 0, s[68:69]
	v_lshl_add_u64 v[0:1], v[0:1], 0, v[84:85]
	global_load_dwordx4 v[28:31], v[24:25], off offset:16
	global_load_dwordx2 v[96:97], v[0:1], off offset:1024
	v_or_b32_e32 v0, 16, v2
	v_sub_u32_e32 v1, 0x7ff, v0
	v_cndmask_b32_e64 v0, v1, v0, s[0:1]
	v_ashrrev_i32_e32 v1, 31, v0
	v_lshl_add_u64 v[0:1], s[18:19], 0, v[0:1]
	v_mad_u64_u32 v[20:21], s[16:17], v0, s53, v[20:21]
	v_mad_i32_i24 v21, v1, s53, v21
	v_lshl_add_u64 v[0:1], v[20:21], 0, s[94:95]
	v_lshl_add_u64 v[0:1], v[0:1], 0, v[82:83]
	v_lshl_add_u64 v[22:23], v[20:21], 0, s[70:71]
	global_load_dword v121, v[0:1], off
	global_load_dword v120, v[0:1], off offset:512
	global_load_dwordx4 v[24:27], v[22:23], off
	v_lshl_add_u64 v[0:1], v[20:21], 0, s[68:69]
	v_lshl_add_u64 v[0:1], v[0:1], 0, v[84:85]
	global_load_dwordx4 v[20:23], v[22:23], off offset:16
	s_nop 0
	global_load_dwordx2 v[92:93], v[0:1], off offset:1024
	s_cmp_lg_u32 s35, 0
	s_cselect_b64 s[16:17], -1, 0
	s_and_b64 s[20:21], s[4:5], s[16:17]
	s_and_saveexec_b64 s[16:17], s[20:21]
	s_cbranch_execz .LBB0_682
	s_sub_i32 s20, s28, 32
	s_sub_i32 vcc_lo, 0x7e0, s20
	s_cmp_lg_u64 s[0:1], 0
	s_cselect_b32 vcc_lo, s20, vcc_lo
	s_add_i32 vcc_lo, vcc_lo, s18
	s_lshl_b32 vcc_lo, vcc_lo, 11
	s_add_u32 s24, s48, vcc_lo
	s_addc_u32 s25, s49, 0
	v_add_u32_e32 v160, v107, v166
	v_add_u32_e32 v161, v106, v166
	ds_read_b64 v[162:163], v160
	ds_read_b64 v[164:165], v161
	s_waitcnt lgkmcnt(1)
	global_store_dwordx2 v167, v[162:163], s[24:25]
	s_waitcnt lgkmcnt(0)
	global_store_dwordx2 v168, v[164:165], s[24:25]
	s_or_b64 exec, exec, s[16:17]
	s_waitcnt vmcnt(12)
	s_branch .Llw_join_677a
.LBB0_682:
	s_or_b64 exec, exec, s[16:17]
	s_waitcnt vmcnt(10)
; __device__ __forceinline__ unsigned pk2(float lo, float hi) { f32x2_t v = {lo, hi}; bf16x2_t b = __builtin_convertvector(v, bf16x2_t); return __builtin_bit_cast(unsigned, b); }
; __device__ __forceinline__ bf16_t f2bf(float f) { return (bf16_t)(pk2(f, 0.f) & 0xffffu); }
; __device__ __forceinline__ float lo_bf(unsigned u) { return __uint_as_float(u << 16); }
; __device__ __forceinline__ float hi_bf(unsigned u) { return __uint_as_float(u & 0xffff0000u); }
; __device__ __forceinline__ float sigmoidf_(float x) { return __builtin_amdgcn_rcpf(1.f + __expf(-x)); }
; __device__ __forceinline__ float siluf_(float x) { return x * __builtin_amdgcn_rcpf(1.f + __expf(-x)); }
; template <int MODE>
; __device__ void scan_unit(int swave, const Params& p, int j, int b, int h, int dir, char* shm) {
;     ...
;       if (MODE == 0) {
;         float z0 = bav0, z1 = bav1;
;         const unsigned lw[8] = {R.lr0.x, R.lr0.y, R.lr0.z, R.lr0.w, R.lr1.x, R.lr1.y, R.lr1.z, R.lr1.w};
; #pragma unroll
;         for (int e = 0; e < 8; ++e) {
;           const float a0 = lo_bf(lw[e]), a1 = hi_bf(lw[e]);
;           z0 += a0 * wa2r[4 * e] + a1 * wa2r[4 * e + 2];
;           z1 += a0 * wa2r[4 * e + 1] + a1 * wa2r[4 * e + 3];
;         }
;         g0 = (fminf(z0, 0.f) - __logf(1.f + __expf(-fabsf(z0)))) * (1.f / 16.f);
;         g1 = (fminf(z1, 0.f) - __logf(1.f + __expf(-fabsf(z1)))) * (1.f / 16.f);
;       } else {
;         const float f0 = lbv0 + (1.f - lbv0) * sigmoidf_(lo_bf(R.k)), f1 = lbv1 + (1.f - lbv1) * sigmoidf_(hi_bf(R.k));
;         g0 = __logf(fmaxf(f0, 1e-20f)); g1 = __logf(fmaxf(f1, 1e-20f));
;       }
;       float s0, s1;
;       const float cum0 = row_scan(g0, s0), cum1 = row_scan(g1, s1);
;       float q0, q1, k0, k1;
;       if (MODE == 0) { q0 = lo_bf(R.q); q1 = hi_bf(R.q); k0 = lo_bf(R.k) * 0.125f; k1 = hi_bf(R.k) * 0.125f; }
;       else { q0 = siluf_(lo_bf(R.q)); q1 = siluf_(hi_bf(R.q)); k0 = (1.f - lbv0) * sigmoidf_(-lo_bf(R.k)); k1 = (1.f - lbv1) * sigmoidf_(-hi_bf(R.k)); }
;       *(unsigned*)(qin + ti * QS + dp) = pk2(q0 * __expf(cum0), q1 * __expf(cum1));
;       *(unsigned*)(ktil + ti * QS + dp) = pk2(k0 * __expf(-cum0), k1 * __expf(-cum1));
;       koutT[dp * 16 + ti] = f2bf(k0 * __expf(s0 - cum0));
;       koutT[(dp + 1) * 16 + ti] = f2bf(k1 * __expf(s1 - cum1));
;       if (ti == 0) *(float2*)(dec + dp) = make_float2(__expf(s0), __expf(s1));
.Llw_join_677a:
	v_and_b32_e32 v1, 0xffff0000, v16
	v_lshlrev_b32_e32 v0, 16, v16
	v_mul_f32_e32 v2, v54, v1
	v_mul_f32_e32 v1, v55, v1
	v_fmac_f32_e32 v1, v53, v0
	v_and_b32_e32 v16, 0xffff0000, v17
	v_fmac_f32_e32 v2, v52, v0
	v_add_f32_e32 v0, v81, v1
	v_lshlrev_b32_e32 v1, 16, v17
	v_mul_f32_e32 v17, v58, v16
	v_mul_f32_e32 v16, v59, v16
	v_fmac_f32_e32 v16, v57, v1
	v_add_f32_e32 v2, v80, v2
	v_fmac_f32_e32 v17, v56, v1
	v_add_f32_e32 v0, v16, v0
	v_and_b32_e32 v16, 0xffff0000, v18
	v_add_f32_e32 v2, v17, v2
	v_lshlrev_b32_e32 v1, 16, v18
	v_mul_f32_e32 v17, v68, v16
	v_mul_f32_e32 v16, v69, v16
	v_fmac_f32_e32 v16, v77, v1
	v_fmac_f32_e32 v17, v76, v1
	v_add_f32_e32 v0, v16, v0
	v_and_b32_e32 v16, 0xffff0000, v19
	v_add_f32_e32 v2, v17, v2
	v_lshlrev_b32_e32 v1, 16, v19
	v_mul_f32_e32 v17, v72, v16
	v_mul_f32_e32 v16, v73, v16
	v_fmac_f32_e32 v17, v70, v1
	v_fmac_f32_e32 v16, v71, v1
	v_lshlrev_b32_e32 v1, 16, v12
	v_and_b32_e32 v12, 0xffff0000, v12
	v_add_f32_e32 v0, v16, v0
	v_mul_f32_e32 v16, v62, v12
	v_mul_f32_e32 v12, v63, v12
	v_add_f32_e32 v2, v17, v2
	v_fmac_f32_e32 v16, v60, v1
	v_fmac_f32_e32 v12, v61, v1
	v_and_b32_e32 v1, 0xffff0000, v13
	v_add_f32_e32 v2, v16, v2
	v_add_f32_e32 v16, v12, v0
	v_lshlrev_b32_e32 v0, 16, v13
	v_mul_f32_e32 v12, v66, v1
	v_fmac_f32_e32 v12, v64, v0
	v_add_f32_e32 v2, v12, v2
	v_mul_f32_e32 v17, v67, v1
	v_and_b32_e32 v13, 0xffff0000, v15
	v_and_b32_e32 v12, 0xffff0000, v14
	v_fmac_f32_e32 v17, v65, v0
	v_lshlrev_b32_e32 v1, 16, v15
	v_lshlrev_b32_e32 v0, 16, v14
	v_pk_mul_f32 v[14:15], v[78:79], v[12:13]
	v_pk_mul_f32 v[12:13], v[88:89], v[12:13]
	v_pk_fma_f32 v[14:15], v[74:75], v[0:1], v[14:15]
	v_pk_fma_f32 v[0:1], v[86:87], v[0:1], v[12:13]
	v_add_f32_e32 v2, v14, v2
	v_add_f32_e32 v2, v15, v2
	v_mul_f32_e64 v14, |v2|, s56
	v_exp_f32_e32 v14, v14
	v_add_f32_e32 v15, v17, v16
	v_add_f32_e32 v0, v0, v15
	v_add_f32_e32 v0, v1, v0
	v_add_f32_e32 v12, 1.0, v14
	v_cmp_gt_f32_e32 vcc, s26, v12
	v_min_f32_e32 v1, 0, v2
	v_lshlrev_b32_e32 v14, 16, v118
	v_cndmask_b32_e64 v13, 0, 32, vcc
	v_ldexp_f32 v12, v12, v13
	v_log_f32_e32 v12, v12
	v_mul_f32_e64 v13, |v0|, s56
	v_exp_f32_e32 v13, v13
	v_min_f32_e32 v0, 0, v0
	v_mul_f32_e32 v2, 0x3f317217, v12
	v_fma_f32 v2, v12, s31, -v2
	v_fmac_f32_e32 v2, 0x3377d1cf, v12
	v_fmac_f32_e32 v2, 0x3f317217, v12
	v_cmp_lt_f32_e64 s[16:17], |v12|, s27
	v_and_b32_e32 v15, 0xffff0000, v118
	s_nop 0
	v_cndmask_b32_e64 v2, v12, v2, s[16:17]
	v_cndmask_b32_e32 v12, 0, v157, vcc
	v_sub_f32_e32 v2, v2, v12
	v_add_f32_e32 v12, 1.0, v13
	v_cmp_gt_f32_e32 vcc, s26, v12
	v_sub_f32_e32 v1, v1, v2
	v_mul_f32_e32 v2, 0x3d800000, v1
	v_cndmask_b32_e64 v13, 0, 32, vcc
	v_ldexp_f32 v12, v12, v13
	v_log_f32_e32 v12, v12
	s_nop 0
	v_mul_f32_e32 v13, 0x3f317217, v12
	v_fma_f32 v13, v12, s31, -v13
	v_fmac_f32_e32 v13, 0x3377d1cf, v12
	v_fmac_f32_e32 v13, 0x3f317217, v12
	v_cmp_lt_f32_e64 s[16:17], |v12|, s27
	s_nop 1
	v_cndmask_b32_e64 v12, v12, v13, s[16:17]
	v_cndmask_b32_e32 v13, 0, v157, vcc
	v_sub_f32_e32 v12, v12, v13
	v_sub_f32_e32 v12, v0, v12
	v_mul_f32_e32 v13, 0x3d800000, v12
	v_mov_b32_dpp v0, v2 row_shr:1 row_mask:0xf bank_mask:0xf bound_ctrl:1
	v_fmac_f32_e32 v0, 0x3d800000, v1
	v_mov_b32_dpp v1, v13 row_shr:1 row_mask:0xf bank_mask:0xf bound_ctrl:1
	v_fmac_f32_e32 v1, 0x3d800000, v12
	v_add_f32_dpp v0, v0, v0 row_shr:2 row_mask:0xf bank_mask:0xf bound_ctrl:1
	v_lshlrev_b32_e32 v12, 16, v119
	v_add_f32_dpp v1, v1, v1 row_shr:2 row_mask:0xf bank_mask:0xf bound_ctrl:1
	v_add_f32_dpp v0, v0, v0 row_shr:4 row_mask:0xf bank_mask:0xf bound_ctrl:1
	v_and_b32_e32 v13, 0xffff0000, v119
	v_add_f32_dpp v1, v1, v1 row_shr:4 row_mask:0xf bank_mask:0xf bound_ctrl:1
	v_add_f32_dpp v2, v0, v0 row_shr:8 row_mask:0xf bank_mask:0xf bound_ctrl:1
	v_mul_f32_e32 v16, 0x3fb8aa3b, v2
	v_add_f32_dpp v124, v1, v1 row_shr:8 row_mask:0xf bank_mask:0xf bound_ctrl:1
	v_mul_f32_e32 v17, 0x3fb8aa3b, v124
	v_exp_f32_e32 v16, v16
	v_exp_f32_e32 v17, v17
	ds_bpermute_b32 v0, v100, v2
	v_mul_f32_e32 v18, 0xbfb8aa3b, v2
	v_mul_f32_e32 v19, 0xbfb8aa3b, v124
	v_exp_f32_e32 v18, v18
	v_exp_f32_e32 v19, v19
	ds_bpermute_b32 v1, v100, v124
	v_pk_mul_f32 v[12:13], v[16:17], v[12:13]
	s_mov_b32 s16, 0x3e000000
	v_cvt_pk_bf16_f32 v16, v12, v13
	v_pk_mul_f32 v[12:13], v[14:15], s[16:17] op_sel_hi:[1,0]
	s_waitcnt lgkmcnt(1)
	v_sub_f32_e32 v2, v0, v2
	v_pk_mul_f32 v[14:15], v[12:13], v[18:19]
	v_mul_f32_e32 v2, 0x3fb8aa3b, v2
	v_cvt_pk_bf16_f32 v14, v14, v15
	ds_write2st64_b32 v101, v16, v14 offset0:94 offset1:103
	v_exp_f32_e32 v2, v2
	s_waitcnt lgkmcnt(1)
	v_sub_f32_e32 v14, v1, v124
	v_mul_f32_e32 v14, 0x3fb8aa3b, v14
	v_exp_f32_e32 v14, v14
	v_mul_f32_e32 v2, v12, v2
	v_cvt_pk_bf16_f32 v2, v2, s0
	ds_write_b16 v102, v2 offset:28672
	v_mul_f32_e32 v2, v13, v14
	v_cvt_pk_bf16_f32 v2, v2, s0
	ds_write_b16 v102, v2 offset:28704
	s_and_saveexec_b64 s[16:17], s[14:15]
	s_cbranch_execz .LBB0_684
	v_mul_f32_e32 v1, 0x3fb8aa3b, v1
	v_mul_f32_e32 v0, 0x3fb8aa3b, v0
	v_exp_f32_e32 v1, v1
	v_exp_f32_e32 v0, v0
	ds_write_b64 v103, v[0:1] offset:35840

; template <int MODE>
; __device__ void scan_unit(int swave, const Params& p, int j, int b, int h, int dir, char* shm) {
;     ...
;   auto compute = [&](const char* buf, bf16_t* obuf) {
;     const bf16_t* qin = (const bf16_t*)buf; const bf16_t* ktil = (const bf16_t*)(buf + OFF_KT); const bf16_t* koutT = (const bf16_t*)(buf + OFF_KO);
;     const bf16_t* vT = (const bf16_t*)(buf + OFF_VT); const float* dec = (const float*)(buf + OFF_DEC);
;     bf16x8 Asc = {0, 0, 0, 0, 0, 0, 0, 0};
;     if (KS == 1 || wk == 0) {
;       f32x4 sc = {0.f, 0.f, 0.f, 0.f};
; #pragma unroll
;       for (int m = 0; m < DK / 32; ++m) {
;         const bf16x8 a = *(const bf16x8*)(ktil + r * QS + m * 32 + q4 * 8);
;         const bf16x8 bb = *(const bf16x8*)(qin + r * QS + m * 32 + q4 * 8);
;         sc = __builtin_amdgcn_mfma_f32_16x16x32_bf16(a, bb, sc, 0, 0, 0);
;       }
;       {
;         const unsigned p01 = pk2(q4 * 4 + 0 > r ? 0.f : sc[0], q4 * 4 + 1 > r ? 0.f : sc[1]);
;         const unsigned p23 = pk2(q4 * 4 + 2 > r ? 0.f : sc[2], q4 * 4 + 3 > r ? 0.f : sc[3]);
;         Asc[0] = (short)(p01 & 0xffff); Asc[1] = (short)(p01 >> 16); Asc[2] = (short)(p23 & 0xffff); Asc[3] = (short)(p23 >> 16);
;       }
;     }
;     bf16x8 Bv[NVT];
; #pragma unroll
;     for (int t = 0; t < NVT; ++t) {
;       const uint2 vv = *(const uint2*)(vT + ((vt0 + t) * 16 + r) * VS + q4 * 4);
;       Bv[t] = (bf16x8){(short)(vv.x & 0xffff), (short)(vv.x >> 16), (short)(vv.y & 0xffff), (short)(vv.y >> 16), 0, 0, 0, 0};
;     }
;     bf16x8 Aq[2];
; #pragma unroll
;     for (int m = 0; m < 2; ++m) {
;       const uint2 lo = *(const uint2*)(qin + r * QS + slab + (2 * m) * 16 + q4 * 4);
;       const uint2 hi = *(const uint2*)(qin + r * QS + slab + (2 * m + 1) * 16 + q4 * 4);
;       Aq[m] = (bf16x8){(short)(lo.x & 0xffff), (short)(lo.x >> 16), (short)(lo.y & 0xffff), (short)(lo.y >> 16),
;                        (short)(hi.x & 0xffff), (short)(hi.x >> 16), (short)(hi.y & 0xffff), (short)(hi.y >> 16)};
;     }
;     f32x4 o[NVT];
; #pragma unroll
;     for (int t = 0; t < NVT; ++t) {
;       o[t] = (f32x4){0.f, 0.f, 0.f, 0.f};
;       if (KS == 1 || wk == 0) o[t] = __builtin_amdgcn_mfma_f32_16x16x32_bf16(Asc, Bv[t], o[t], 0, 0, 0);
;     }
; #pragma unroll
;     for (int m = 0; m < 2; ++m)
; #pragma unroll
;       for (int t = 0; t < NVT; ++t) {
;         const f32x4 s0 = S[2 * m][t], s1 = S[2 * m + 1][t];
.LBB0_686:
	s_or_b64 exec, exec, s[16:17]
	ds_write_b16 v104, v90 offset:42752
	ds_write_b16_d16_hi v104, v90 offset:42792
	ds_write_b16 v104, v91 offset:42832
	ds_write_b16_d16_hi v104, v91 offset:42872
	ds_read_b128 v[4:7], v108 offset:2304
	ds_read_b128 v[8:11], v108
	ds_read_b128 v[12:15], v108 offset:2368
	ds_read_b128 v[16:19], v108 offset:64
	v_mov_b32_e32 v2, v3
	v_mov_b32_e32 v128, v3
	s_waitcnt lgkmcnt(2)
	v_mfma_f32_16x16x32_bf16 v[4:7], v[4:7], v[8:11], 0
	ds_read_b64 v[8:9], v109 offset:6656
	ds_read2_b64 v[116:119], v115 offset1:4
	ds_read2_b64 v[124:127], v115 offset0:8 offset1:12
	v_mov_b32_e32 v10, v3
	v_mov_b32_e32 v11, v3
	s_waitcnt lgkmcnt(3)
	v_mfma_f32_16x16x32_bf16 v[4:7], v[12:15], v[16:19], v[4:7]
	s_waitcnt lgkmcnt(1)
	v_bfi_b32 v118, s30, v118, v118
	s_waitcnt lgkmcnt(0)
	v_bfi_b32 v126, s30, v126, v126
	v_cvt_pk_bf16_f32 v12, v48, v49
	v_cvt_pk_bf16_f32 v13, v50, v51
	v_cvt_pk_bf16_f32 v14, v44, v45
	s_nop 0
	v_cndmask_b32_e64 v0, v4, 0, s[6:7]
	v_cndmask_b32_e64 v1, 0, v5, s[8:9]
	v_cndmask_b32_e64 v4, v6, 0, s[10:11]
	v_cndmask_b32_e64 v5, v7, 0, s[12:13]
	v_cvt_pk_bf16_f32 v0, v0, v1
	v_cvt_pk_bf16_f32 v1, v4, v5
	v_cvt_pk_bf16_f32 v15, v46, v47
	v_mov_b32_e32 v129, v3
	v_mfma_f32_16x16x32_bf16 v[4:7], v[0:3], v[8:11], 0
	v_mfma_f32_16x16x32_bf16 v[4:7], v[116:119], v[12:15], v[4:7]
	v_cvt_pk_bf16_f32 v12, v40, v41
	v_cvt_pk_bf16_f32 v13, v42, v43
	v_cvt_pk_bf16_f32 v14, v36, v37
	v_cvt_pk_bf16_f32 v15, v38, v39
	s_nop 1
	v_mfma_f32_16x16x32_bf16 v[4:7], v[124:127], v[12:15], v[4:7]
	v_add_u32_e32 v124, 0x100, v111
	s_nop 6
	v_cvt_pk_bf16_f32 v0, v4, s0
	v_cvt_pk_bf16_f32 v1, v5, s0
	ds_write_b16 v110, v0 offset:48128
	ds_write_b16 v110, v1 offset:48392
	v_cvt_pk_bf16_f32 v0, v6, s0
	ds_write_b16 v110, v0 offset:48656
	v_cvt_pk_bf16_f32 v0, v7, s0
	ds_write_b16 v110, v0 offset:48920
	ds_read2st64_b64 v[4:7], v111 offset0:9 offset1:10
	ds_read2st64_b64 v[12:15], v111 offset0:11 offset1:12
	ds_read_b128 v[16:19], v112 offset:11776
	ds_read_b128 v[116:119], v112 offset:11840
	s_waitcnt lgkmcnt(3)
	v_mov_b32_e32 v0, v4
	v_mov_b32_e32 v1, v5
	s_waitcnt lgkmcnt(1)
	v_pk_mul_f32 v[18:19], v[50:51], v[18:19]
	v_pk_mul_f32 v[16:17], v[48:49], v[16:17]
	s_waitcnt lgkmcnt(0)
	v_pk_mul_f32 v[4:5], v[44:45], v[116:117]
	ds_read_b128 v[48:51], v112 offset:11968
	v_mfma_f32_16x16x16_bf16 v[16:19], v[0:1], v[8:9], v[16:19]
	v_mov_b32_e32 v0, v6
	v_mov_b32_e32 v1, v7
	v_pk_mul_f32 v[6:7], v[46:47], v[118:119]
	ds_read_b128 v[44:47], v112 offset:11904
	s_waitcnt lgkmcnt(0)
	v_pk_mul_f32 v[42:43], v[42:43], v[46:47]
	v_mfma_f32_16x16x16_bf16 v[4:7], v[0:1], v[8:9], v[4:7]
	v_pk_mul_f32 v[40:41], v[40:41], v[44:45]
	s_nop 1
	v_mfma_f32_16x16x16_bf16 v[116:119], v[12:13], v[8:9], v[40:43]
	v_mov_b32_e32 v0, v14
	v_mov_b32_e32 v1, v15
	ds_read_b128 v[12:15], v108 offset:14336
	v_pk_mul_f32 v[38:39], v[38:39], v[50:51]
	v_pk_mul_f32 v[36:37], v[36:37], v[48:49]
	s_nop 1
	v_mfma_f32_16x16x16_bf16 v[8:11], v[0:1], v[8:9], v[36:39]
	s_nop 2
	ds_read_b128 v[36:39], v108 offset:14400
	ds_read_b128 v[40:43], v108 offset:12032
	ds_read_b128 v[44:47], v108 offset:12096
	s_waitcnt lgkmcnt(1)
	v_mfma_f32_16x16x32_bf16 v[12:15], v[12:15], v[40:43], 0
	s_waitcnt lgkmcnt(0)
	v_mfma_f32_16x16x32_bf16 v[12:15], v[36:39], v[44:47], v[12:15]
	v_add_u32_e32 v36, 0x2800, v115
	v_cvt_pk_bf16_f32 v44, v16, v17
	v_cvt_pk_bf16_f32 v45, v18, v19
	v_cvt_pk_bf16_f32 v46, v4, v5
	v_cvt_pk_bf16_f32 v47, v6, v7
	s_nop 2
	v_cndmask_b32_e64 v0, v12, 0, s[6:7]
	v_cndmask_b32_e64 v1, 0, v13, s[8:9]
	v_cvt_pk_bf16_f32 v0, v0, v1
	v_cndmask_b32_e64 v1, v14, 0, s[10:11]
	v_cndmask_b32_e64 v2, v15, 0, s[12:13]
	ds_read2_b64 v[12:15], v36 offset0:224 offset1:228
	ds_read2_b64 v[36:39], v36 offset0:232 offset1:236
	v_cvt_pk_bf16_f32 v1, v1, v2
	ds_read_b64 v[126:127], v109 offset:18688
	v_mov_b32_e32 v2, v3
	s_waitcnt lgkmcnt(2)
	v_bfi_b32 v14, s30, v14, v14
	s_waitcnt lgkmcnt(1)
	v_bfi_b32 v38, s30, v38, v38
	s_waitcnt lgkmcnt(0)
	v_mfma_f32_16x16x32_bf16 v[40:43], v[0:3], v[126:129], 0
	v_mfma_f32_16x16x32_bf16 v[12:15], v[12:15], v[44:47], v[40:43]
	s_nop 6
	v_cvt_pk_bf16_f32 v40, v116, v117
	v_cvt_pk_bf16_f32 v41, v118, v119
	v_cvt_pk_bf16_f32 v42, v8, v9
	v_cvt_pk_bf16_f32 v43, v10, v11
	s_nop 1
	v_mfma_f32_16x16x32_bf16 v[12:15], v[36:39], v[40:43], v[12:15]
	s_nop 7
	v_cvt_pk_bf16_f32 v0, v12, s0
	ds_write_b16 v110, v0 offset:52352
	v_cvt_pk_bf16_f32 v0, v13, s0
	ds_write_b16 v110, v0 offset:52616
	v_cvt_pk_bf16_f32 v0, v14, s0
	ds_write_b16 v110, v0 offset:52880
	v_cvt_pk_bf16_f32 v0, v15, s0
	ds_write_b16 v110, v0 offset:53144
	ds_read2st64_b64 v[12:15], v124 offset0:32 offset1:33
	ds_read2st64_b64 v[36:39], v124 offset0:34 offset1:35
	ds_read_b128 v[40:43], v112 offset:23808
	ds_read_b128 v[44:47], v112 offset:23872
	s_waitcnt lgkmcnt(3)
	s_waitcnt lgkmcnt(1)
	v_pk_mul_f32 v[18:19], v[18:19], v[42:43]
	v_pk_mul_f32 v[16:17], v[16:17], v[40:41]
	s_waitcnt lgkmcnt(0)
	v_pk_mul_f32 v[6:7], v[6:7], v[46:47]
	v_pk_mul_f32 v[4:5], v[4:5], v[44:45]
	v_mfma_f32_16x16x16_bf16 v[40:43], v[12:13], v[126:127], v[16:19]
	v_mov_b32_e32 v0, v14
	v_mov_b32_e32 v1, v15
	ds_read_b128 v[12:15], v112 offset:24000
	s_nop 0
	v_mfma_f32_16x16x16_bf16 v[44:47], v[0:1], v[126:127], v[4:7]
	s_nop 1
	ds_read_b128 v[4:7], v112 offset:23936
	s_waitcnt lgkmcnt(0)
	s_barrier
; template <int MODE>
; __device__ void scan_unit(int swave, const Params& p, int j, int b, int h, int dir, char* shm) {
;     ...
;   auto load_raw = [&](int c, Raw& R) {
;     const int tok = tokof(c, ti);
;     const bf16_t* row = P + (rowbase + tok) * LDP;
;     if (MODE == 0) {
;       R.q = *(const unsigned*)(row + E_GQ + h * 64 + dp); R.k = *(const unsigned*)(row + E_GK + h * 64 + dp);
;       const uint4* lrp = (const uint4*)(row + (dir ? E_GLB : E_GLF));
;       R.lr0 = lrp[0]; R.lr1 = lrp[1];
;       R.v = *(const uint2*)(row + E_GV + h * 128 + vg * 4);
;     ...
;   auto body = [&](int it, Raw& c0, Raw& c1, Raw& n0, Raw& n1) {
;     touch(c0); touch(c1);
;     __builtin_amdgcn_sched_barrier(0);
;     const int cA = 2 * it + 4 < NCH ? 2 * it + 4 : NCH - 2;
;     load_raw(cA, n0); load_raw(cA + 1, n1);
;     if (it > 0) { ostore(2 * it - 2, obp((it - 1) & 1, 0)); ostore(2 * it - 1, obp((it - 1) & 1, 1)); }
;     stage2(c0, bufp((it + 1) & 1, 0), 0); stage2(c1, bufp((it + 1) & 1, 1), 0);
	s_waitcnt lgkmcnt(0)
	v_pk_mul_f32 v[6:7], v[118:119], v[6:7]
	v_pk_mul_f32 v[4:5], v[116:117], v[4:5]
	s_nop 1
	v_mfma_f32_16x16x16_bf16 v[48:51], v[36:37], v[126:127], v[4:7]
	v_mov_b32_e32 v0, v38
	v_mov_b32_e32 v1, v39
	s_nop 0
	v_pk_mul_f32 v[6:7], v[10:11], v[14:15]
	v_pk_mul_f32 v[4:5], v[8:9], v[12:13]
	s_nop 1
	v_mfma_f32_16x16x16_bf16 v[36:39], v[0:1], v[126:127], v[4:7]
	s_add_i32 s16, s28, 0x60
	s_and_b64 s[2:3], s[2:3], exec
	s_cselect_b32 s2, s16, 0x7e0
	v_or_b32_e32 v2, s2, v99
	v_sub_u32_e32 v0, 0x7ff, v2
	v_cndmask_b32_e64 v0, v0, v2, s[0:1]
	v_ashrrev_i32_e32 v1, 31, v0
	v_lshl_add_u64 v[0:1], s[18:19], 0, v[0:1]
	v_mov_b64_e32 v[4:5], s[46:47]
	v_mad_u64_u32 v[6:7], s[2:3], v0, s53, v[4:5]
	v_mad_i32_i24 v7, v1, s53, v7
	v_lshl_add_u64 v[0:1], v[6:7], 0, s[94:95]
	v_lshl_add_u64 v[0:1], v[0:1], 0, v[82:83]
	s_mov_b32 s45, s95
	s_mov_b32 s51, s95
	v_lshl_add_u64 v[8:9], v[6:7], 0, s[44:45]
	global_load_dword v119, v[0:1], off
	global_load_dword v118, v[0:1], off offset:512
	global_load_dwordx4 v[16:19], v[8:9], off
	v_lshl_add_u64 v[0:1], v[6:7], 0, s[50:51]
	v_lshl_add_u64 v[0:1], v[0:1], 0, v[84:85]
	global_load_dwordx4 v[12:15], v[8:9], off offset:16
	global_load_dwordx2 v[94:95], v[0:1], off offset:1024
	v_or_b32_e32 v0, 16, v2
	v_sub_u32_e32 v1, 0x7ff, v0
	v_cndmask_b32_e64 v0, v1, v0, s[0:1]
	v_ashrrev_i32_e32 v1, 31, v0
	v_lshl_add_u64 v[0:1], s[18:19], 0, v[0:1]
	v_mad_u64_u32 v[4:5], s[2:3], v0, s53, v[4:5]
	v_mad_i32_i24 v5, v1, s53, v5
	v_lshl_add_u64 v[0:1], v[4:5], 0, s[94:95]
	v_lshl_add_u64 v[0:1], v[0:1], 0, v[82:83]
	v_lshl_add_u64 v[6:7], v[4:5], 0, s[44:45]
	global_load_dword v117, v[0:1], off
	global_load_dword v116, v[0:1], off offset:512
	global_load_dwordx4 v[8:11], v[6:7], off
	v_lshl_add_u64 v[0:1], v[4:5], 0, s[50:51]
	v_lshl_add_u64 v[0:1], v[0:1], 0, v[84:85]
	global_load_dwordx4 v[4:7], v[6:7], off offset:16
	s_nop 0
	global_load_dwordx2 v[90:91], v[0:1], off offset:1024
	s_and_saveexec_b64 s[2:3], s[4:5]
	s_cbranch_execz .LBB0_691
	s_sub_i32 vcc_lo, 0x7e0, s28
	s_cmp_lg_u64 s[0:1], 0
	s_cselect_b32 vcc_lo, s28, vcc_lo
	s_add_i32 vcc_lo, vcc_lo, s18
	s_lshl_b32 vcc_lo, vcc_lo, 11
	s_add_u32 s16, s48, vcc_lo
	s_addc_u32 s17, s49, 0
	v_add_u32_e32 v160, v113, v166
	v_add_u32_e32 v161, v114, v166
	ds_read_b64 v[162:163], v160
	ds_read_b64 v[164:165], v161
	s_waitcnt lgkmcnt(1)
	global_store_dwordx2 v167, v[162:163], s[16:17]
	s_waitcnt lgkmcnt(0)
	global_store_dwordx2 v168, v[164:165], s[16:17]
	s_or_b64 exec, exec, s[2:3]
	s_waitcnt vmcnt(12)
	s_branch .Llw_join_677b
.LBB0_691:
	s_or_b64 exec, exec, s[2:3]
	s_waitcnt vmcnt(10)
; __device__ __forceinline__ unsigned pk2(float lo, float hi) { f32x2_t v = {lo, hi}; bf16x2_t b = __builtin_convertvector(v, bf16x2_t); return __builtin_bit_cast(unsigned, b); }
; __device__ __forceinline__ bf16_t f2bf(float f) { return (bf16_t)(pk2(f, 0.f) & 0xffffu); }
; __device__ __forceinline__ float lo_bf(unsigned u) { return __uint_as_float(u << 16); }
; __device__ __forceinline__ float hi_bf(unsigned u) { return __uint_as_float(u & 0xffff0000u); }
; __device__ __forceinline__ float sigmoidf_(float x) { return __builtin_amdgcn_rcpf(1.f + __expf(-x)); }
; __device__ __forceinline__ float siluf_(float x) { return x * __builtin_amdgcn_rcpf(1.f + __expf(-x)); }
; template <int MODE>
; __device__ void scan_unit(int swave, const Params& p, int j, int b, int h, int dir, char* shm) {
;     ...
;       if (MODE == 0) {
;         float z0 = bav0, z1 = bav1;
;         const unsigned lw[8] = {R.lr0.x, R.lr0.y, R.lr0.z, R.lr0.w, R.lr1.x, R.lr1.y, R.lr1.z, R.lr1.w};
; #pragma unroll
;         for (int e = 0; e < 8; ++e) {
;           const float a0 = lo_bf(lw[e]), a1 = hi_bf(lw[e]);
;           z0 += a0 * wa2r[4 * e] + a1 * wa2r[4 * e + 2];
;           z1 += a0 * wa2r[4 * e + 1] + a1 * wa2r[4 * e + 3];
;         }
;         g0 = (fminf(z0, 0.f) - __logf(1.f + __expf(-fabsf(z0)))) * (1.f / 16.f);
;         g1 = (fminf(z1, 0.f) - __logf(1.f + __expf(-fabsf(z1)))) * (1.f / 16.f);
;       } else {
;         const float f0 = lbv0 + (1.f - lbv0) * sigmoidf_(lo_bf(R.k)), f1 = lbv1 + (1.f - lbv1) * sigmoidf_(hi_bf(R.k));
;         g0 = __logf(fmaxf(f0, 1e-20f)); g1 = __logf(fmaxf(f1, 1e-20f));
;       }
;       float s0, s1;
;       const float cum0 = row_scan(g0, s0), cum1 = row_scan(g1, s1);
;       float q0, q1, k0, k1;
;       if (MODE == 0) { q0 = lo_bf(R.q); q1 = hi_bf(R.q); k0 = lo_bf(R.k) * 0.125f; k1 = hi_bf(R.k) * 0.125f; }
;       else { q0 = siluf_(lo_bf(R.q)); q1 = siluf_(hi_bf(R.q)); k0 = (1.f - lbv0) * sigmoidf_(-lo_bf(R.k)); k1 = (1.f - lbv1) * sigmoidf_(-hi_bf(R.k)); }
;       *(unsigned*)(qin + ti * QS + dp) = pk2(q0 * __expf(cum0), q1 * __expf(cum1));
;       *(unsigned*)(ktil + ti * QS + dp) = pk2(k0 * __expf(-cum0), k1 * __expf(-cum1));
;       koutT[dp * 16 + ti] = f2bf(k0 * __expf(s0 - cum0));
;       koutT[(dp + 1) * 16 + ti] = f2bf(k1 * __expf(s1 - cum1));
;       if (ti == 0) *(float2*)(dec + dp) = make_float2(__expf(s0), __expf(s1));
.Llw_join_677b:
	v_and_b32_e32 v1, 0xffff0000, v32
	v_lshlrev_b32_e32 v0, 16, v32
	v_mul_f32_e32 v2, v54, v1
	v_mul_f32_e32 v1, v55, v1
	v_fmac_f32_e32 v1, v53, v0
	v_and_b32_e32 v32, 0xffff0000, v33
	v_fmac_f32_e32 v2, v52, v0
	v_add_f32_e32 v0, v81, v1
	v_lshlrev_b32_e32 v1, 16, v33
	v_mul_f32_e32 v33, v58, v32
	v_mul_f32_e32 v32, v59, v32
	v_fmac_f32_e32 v32, v57, v1
	v_add_f32_e32 v2, v80, v2
	v_fmac_f32_e32 v33, v56, v1
	v_add_f32_e32 v0, v0, v32
	v_and_b32_e32 v32, 0xffff0000, v34
	v_add_f32_e32 v2, v2, v33
	v_lshlrev_b32_e32 v1, 16, v34
	v_mul_f32_e32 v33, v68, v32
	v_mul_f32_e32 v32, v69, v32
	v_fmac_f32_e32 v32, v77, v1
	v_fmac_f32_e32 v33, v76, v1
	v_add_f32_e32 v0, v0, v32
	v_and_b32_e32 v32, 0xffff0000, v35
	v_add_f32_e32 v2, v2, v33
	v_lshlrev_b32_e32 v1, 16, v35
	v_mul_f32_e32 v33, v72, v32
	v_mul_f32_e32 v32, v73, v32
	v_fmac_f32_e32 v33, v70, v1
	v_fmac_f32_e32 v32, v71, v1
	v_lshlrev_b32_e32 v1, 16, v28
	v_and_b32_e32 v28, 0xffff0000, v28
	v_add_f32_e32 v0, v0, v32
	v_mul_f32_e32 v32, v62, v28
	v_mul_f32_e32 v28, v63, v28
	v_add_f32_e32 v2, v2, v33
	v_fmac_f32_e32 v32, v60, v1
	v_fmac_f32_e32 v28, v61, v1
	v_and_b32_e32 v1, 0xffff0000, v29
	v_add_f32_e32 v2, v2, v32
	v_add_f32_e32 v32, v0, v28
	v_lshlrev_b32_e32 v0, 16, v29
	v_mul_f32_e32 v28, v66, v1
	v_fmac_f32_e32 v28, v64, v0
	v_add_f32_e32 v2, v2, v28
	v_mul_f32_e32 v33, v67, v1
	v_and_b32_e32 v29, 0xffff0000, v31
	v_and_b32_e32 v28, 0xffff0000, v30
	v_fmac_f32_e32 v33, v65, v0
	v_lshlrev_b32_e32 v1, 16, v31
	v_lshlrev_b32_e32 v0, 16, v30
	v_pk_mul_f32 v[30:31], v[78:79], v[28:29]
	v_pk_mul_f32 v[28:29], v[88:89], v[28:29]
	v_pk_fma_f32 v[30:31], v[74:75], v[0:1], v[30:31]
	v_pk_fma_f32 v[0:1], v[86:87], v[0:1], v[28:29]
	v_add_f32_e32 v2, v2, v30
	v_add_f32_e32 v2, v2, v31
	v_mul_f32_e64 v30, |v2|, s56
	v_exp_f32_e32 v30, v30
	v_add_f32_e32 v31, v32, v33
	v_add_f32_e32 v0, v31, v0
	v_add_f32_e32 v0, v0, v1
	v_add_f32_e32 v28, 1.0, v30
	v_cmp_gt_f32_e32 vcc, s26, v28
	v_min_f32_e32 v1, 0, v2
	v_lshlrev_b32_e32 v30, 16, v122
	v_cndmask_b32_e64 v29, 0, 32, vcc
	v_ldexp_f32 v28, v28, v29
	v_log_f32_e32 v28, v28
	v_mul_f32_e64 v29, |v0|, s56
	v_exp_f32_e32 v29, v29
	v_min_f32_e32 v0, 0, v0
	v_mul_f32_e32 v2, 0x3f317217, v28
	v_fma_f32 v2, v28, s31, -v2
	v_fmac_f32_e32 v2, 0x3377d1cf, v28
	v_fmac_f32_e32 v2, 0x3f317217, v28
	v_cmp_lt_f32_e64 s[16:17], |v28|, s27
	v_and_b32_e32 v31, 0xffff0000, v122
	s_mov_b32 s2, 0x3e000000
	v_cndmask_b32_e64 v2, v28, v2, s[16:17]
	v_cndmask_b32_e32 v28, 0, v157, vcc
	v_sub_f32_e32 v2, v2, v28
	v_add_f32_e32 v28, 1.0, v29
	v_cmp_gt_f32_e32 vcc, s26, v28
	v_sub_f32_e32 v1, v1, v2
	v_mul_f32_e32 v2, 0x3d800000, v1
	v_cndmask_b32_e64 v29, 0, 32, vcc
	v_ldexp_f32 v28, v28, v29
	v_log_f32_e32 v28, v28
	s_nop 0
	v_mul_f32_e32 v29, 0x3f317217, v28
	v_fma_f32 v29, v28, s31, -v29
	v_fmac_f32_e32 v29, 0x3377d1cf, v28
	v_fmac_f32_e32 v29, 0x3f317217, v28
	v_cmp_lt_f32_e64 s[16:17], |v28|, s27
	s_nop 1
	v_cndmask_b32_e64 v28, v28, v29, s[16:17]
	v_cndmask_b32_e32 v29, 0, v157, vcc
	v_sub_f32_e32 v28, v28, v29
	v_sub_f32_e32 v28, v0, v28
	v_mul_f32_e32 v29, 0x3d800000, v28
	v_mov_b32_dpp v0, v2 row_shr:1 row_mask:0xf bank_mask:0xf bound_ctrl:1
	v_fmac_f32_e32 v0, 0x3d800000, v1
	v_mov_b32_dpp v1, v29 row_shr:1 row_mask:0xf bank_mask:0xf bound_ctrl:1
	v_fmac_f32_e32 v1, 0x3d800000, v28
	v_add_f32_dpp v0, v0, v0 row_shr:2 row_mask:0xf bank_mask:0xf bound_ctrl:1
	v_lshlrev_b32_e32 v28, 16, v123
	v_add_f32_dpp v1, v1, v1 row_shr:2 row_mask:0xf bank_mask:0xf bound_ctrl:1
	v_add_f32_dpp v0, v0, v0 row_shr:4 row_mask:0xf bank_mask:0xf bound_ctrl:1
	v_and_b32_e32 v29, 0xffff0000, v123
	v_add_f32_dpp v1, v1, v1 row_shr:4 row_mask:0xf bank_mask:0xf bound_ctrl:1
	v_add_f32_dpp v2, v0, v0 row_shr:8 row_mask:0xf bank_mask:0xf bound_ctrl:1
	v_mul_f32_e32 v32, 0x3fb8aa3b, v2
	v_add_f32_dpp v125, v1, v1 row_shr:8 row_mask:0xf bank_mask:0xf bound_ctrl:1
	v_mul_f32_e32 v33, 0x3fb8aa3b, v125
	v_exp_f32_e32 v32, v32
	v_exp_f32_e32 v33, v33
	ds_bpermute_b32 v0, v100, v2
	v_mul_f32_e32 v34, 0xbfb8aa3b, v2
	v_mul_f32_e32 v35, 0xbfb8aa3b, v125
	v_exp_f32_e32 v34, v34
	v_exp_f32_e32 v35, v35
	ds_bpermute_b32 v1, v100, v125
	v_pk_mul_f32 v[28:29], v[32:33], v[28:29]
	s_waitcnt lgkmcnt(1)
	v_sub_f32_e32 v2, v0, v2
	v_cvt_pk_bf16_f32 v32, v28, v29
	v_pk_mul_f32 v[28:29], v[30:31], s[2:3] op_sel_hi:[1,0]
	v_mul_f32_e32 v2, 0x3fb8aa3b, v2
	v_pk_mul_f32 v[30:31], v[28:29], v[34:35]
	v_exp_f32_e32 v2, v2
	v_cvt_pk_bf16_f32 v30, v30, v31
	ds_write2st64_b32 v101, v32, v30 offset1:9
	s_waitcnt lgkmcnt(1)
	v_sub_f32_e32 v30, v1, v125
	v_mul_f32_e32 v30, 0x3fb8aa3b, v30
	v_exp_f32_e32 v30, v30
	v_mul_f32_e32 v2, v28, v2
	v_cvt_pk_bf16_f32 v2, v2, s0
	ds_write_b16 v102, v2 offset:4608
	v_mul_f32_e32 v2, v29, v30
	v_cvt_pk_bf16_f32 v2, v2, s0
	ds_write_b16 v102, v2 offset:4640
	s_and_saveexec_b64 s[2:3], s[14:15]
	s_cbranch_execz .LBB0_693
	v_mul_f32_e32 v1, 0x3fb8aa3b, v1
	v_mul_f32_e32 v0, 0x3fb8aa3b, v0
	v_exp_f32_e32 v1, v1
	v_exp_f32_e32 v0, v0
	ds_write_b64 v103, v[0:1] offset:11776
